# mla_up K/V epilogue: SSQ loads of row groups 1-3 batched into one wait
# speedup vs baseline: 1.0053x; 1.0053x over previous
;     ...
;             for (int mi = 0; mi < MI; ++mi) {
;                 const int tok = tok0 + wr * C::WROWS + mi * 32 + li, tl = tok - half * HALF_T;
;                 const f32x4 s0 = *(const f32x4*)(SSQ + tok * 12 + 8);
;                 const float rs = __builtin_amdgcn_rsqf(((s0.x + s0.y) + (s0.z + s0.w)) * (1.f / 256.f) + EPS);
.LBB0_806:
	s_or_b64 exec, exec, s[4:5]
	v_add_u32_e32 v204, 0x180, v204
	v_ashrrev_i32_e32 v205, 31, v204
	v_lshl_add_u64 v[206:207], v[204:205], 2, s[10:11]
	global_load_dwordx4 v[100:103], v[206:207], off offset:1568
	global_load_dwordx4 v[104:107], v[206:207], off offset:3104
	global_load_dwordx4 v[206:209], v[206:207], off offset:32
	s_waitcnt vmcnt(0)
	v_add_f32_e32 v175, v206, v207
	v_add_f32_e32 v197, v208, v209
	v_add_f32_e32 v175, v175, v197
	v_fmamk_f32 v175, v175, 0x3b800000, v252
	v_rsq_f32_e32 v206, v175
	s_nop 0
	v_mul_f32_e32 v197, v80, v206
	v_mul_f32_e32 v175, v81, v206
	s_and_saveexec_b64 s[4:5], vcc
	s_xor_b64 s[4:5], exec, s[4:5]
	s_cbranch_execz .LBB0_808
; DI bf16_t f2bf(float x) { return (bf16_t)(pk2(x, 0.f) & 0xffffu); }
;     ...
;                     const int bl = tl >> 12, sq = tl & 4095;
; #pragma unroll
;                     for (int ni = 0; ni < 2; ++ni)
; #pragma unroll
;                         for (int r = 0; r < 16; ++r) {
;                             const int n = ncol0 - 2048 + ni * 32 + 8 * (r >> 2) + 4 * h + (r & 3);
;                             VT[((size_t)(bl * 2048 + n)) * 4096 + sq] = f2bf(acc[mi][ni][r] * rs);
;                         }
	s_movk_i32 s18, 0xfff
	v_bitop3_b32 v199, v246, s18, 32 bitop3:0xc8
	v_readlane_b32 s18, v254, 40
	v_lshlrev_b32_e32 v208, 1, v199
	v_mov_b32_e32 v209, v177
	v_readlane_b32 s19, v254, 41
	v_lshlrev_b64 v[214:215], 13, v[192:193]
	v_cvt_pk_bf16_f32 v197, v197, s0
	v_lshl_add_u64 v[208:209], s[18:19], 0, v[208:209]
	v_lshl_add_u64 v[214:215], v[208:209], 0, v[214:215]
	global_store_short v[214:215], v197, off
	v_lshlrev_b64 v[214:215], 13, v[194:195]
	v_cvt_pk_bf16_f32 v175, v175, s0
	v_lshl_add_u64 v[214:215], v[208:209], 0, v[214:215]
	global_store_short v[214:215], v175, off
	v_mul_f32_e32 v175, v82, v206
	v_lshlrev_b64 v[214:215], 13, v[190:191]
	v_cvt_pk_bf16_f32 v175, v175, s0
	v_lshl_add_u64 v[214:215], v[208:209], 0, v[214:215]
	global_store_short v[214:215], v175, off
	v_mul_f32_e32 v175, v83, v206
	v_lshlrev_b64 v[214:215], 13, v[188:189]
	v_cvt_pk_bf16_f32 v175, v175, s0
	v_lshl_add_u64 v[214:215], v[208:209], 0, v[214:215]
	global_store_short v[214:215], v175, off
	v_mul_f32_e32 v175, v84, v206
	v_lshlrev_b64 v[214:215], 13, v[186:187]
	v_cvt_pk_bf16_f32 v175, v175, s0
	v_lshl_add_u64 v[214:215], v[208:209], 0, v[214:215]
	global_store_short v[214:215], v175, off
	v_mul_f32_e32 v175, v85, v206
	v_lshlrev_b64 v[214:215], 13, v[184:185]
	v_cvt_pk_bf16_f32 v175, v175, s0
	v_lshl_add_u64 v[214:215], v[208:209], 0, v[214:215]
	global_store_short v[214:215], v175, off
	v_mul_f32_e32 v175, v86, v206
	v_lshlrev_b64 v[214:215], 13, v[182:183]
	v_cvt_pk_bf16_f32 v175, v175, s0
	v_lshl_add_u64 v[214:215], v[208:209], 0, v[214:215]
	global_store_short v[214:215], v175, off
	v_mul_f32_e32 v175, v87, v206
	v_lshlrev_b64 v[214:215], 13, v[180:181]
	v_cvt_pk_bf16_f32 v175, v175, s0
	v_lshl_add_u64 v[214:215], v[208:209], 0, v[214:215]
	global_store_short v[214:215], v175, off
	v_mul_f32_e32 v175, v88, v206
	v_lshlrev_b64 v[214:215], 13, v[178:179]
	v_cvt_pk_bf16_f32 v175, v175, s0
	v_lshl_add_u64 v[214:215], v[208:209], 0, v[214:215]
	global_store_short v[214:215], v175, off
	v_mul_f32_e32 v175, v89, v206
	v_lshlrev_b64 v[214:215], 13, v[172:173]
	v_cvt_pk_bf16_f32 v175, v175, s0
	v_lshl_add_u64 v[214:215], v[208:209], 0, v[214:215]
	global_store_short v[214:215], v175, off
	v_mul_f32_e32 v175, v90, v206
	v_lshlrev_b64 v[214:215], 13, v[170:171]
	v_cvt_pk_bf16_f32 v175, v175, s0
	v_lshl_add_u64 v[214:215], v[208:209], 0, v[214:215]
	global_store_short v[214:215], v175, off
	v_mul_f32_e32 v175, v91, v206
	v_lshlrev_b64 v[214:215], 13, v[168:169]
	v_cvt_pk_bf16_f32 v175, v175, s0
	v_lshl_add_u64 v[214:215], v[208:209], 0, v[214:215]
	global_store_short v[214:215], v175, off
	v_mul_f32_e32 v175, v92, v206
	v_lshlrev_b64 v[214:215], 13, v[166:167]
	v_cvt_pk_bf16_f32 v175, v175, s0
	v_lshl_add_u64 v[214:215], v[208:209], 0, v[214:215]
	global_store_short v[214:215], v175, off
	v_mul_f32_e32 v175, v93, v206
	v_lshlrev_b64 v[214:215], 13, v[164:165]
	v_cvt_pk_bf16_f32 v175, v175, s0
	v_lshl_add_u64 v[214:215], v[208:209], 0, v[214:215]
	global_store_short v[214:215], v175, off
	v_mul_f32_e32 v175, v94, v206
	v_lshlrev_b64 v[214:215], 13, v[162:163]
	v_cvt_pk_bf16_f32 v175, v175, s0
	v_lshl_add_u64 v[214:215], v[208:209], 0, v[214:215]
	global_store_short v[214:215], v175, off
	v_mul_f32_e32 v175, v95, v206
	v_lshlrev_b64 v[214:215], 13, v[160:161]
	v_cvt_pk_bf16_f32 v175, v175, s0
	v_lshl_add_u64 v[214:215], v[208:209], 0, v[214:215]
	global_store_short v[214:215], v175, off
	v_mul_f32_e32 v175, v64, v206
	v_lshlrev_b64 v[214:215], 13, v[158:159]
	v_cvt_pk_bf16_f32 v175, v175, s0
	v_lshl_add_u64 v[214:215], v[208:209], 0, v[214:215]
	global_store_short v[214:215], v175, off
	v_mul_f32_e32 v175, v65, v206
	v_lshlrev_b64 v[214:215], 13, v[156:157]
	v_cvt_pk_bf16_f32 v175, v175, s0
	v_lshl_add_u64 v[214:215], v[208:209], 0, v[214:215]
	global_store_short v[214:215], v175, off
	v_mul_f32_e32 v175, v66, v206
	v_lshlrev_b64 v[214:215], 13, v[154:155]
	v_cvt_pk_bf16_f32 v175, v175, s0
	v_lshl_add_u64 v[214:215], v[208:209], 0, v[214:215]
	global_store_short v[214:215], v175, off
	v_mul_f32_e32 v175, v67, v206
	v_lshlrev_b64 v[214:215], 13, v[152:153]
	v_cvt_pk_bf16_f32 v175, v175, s0
	v_lshl_add_u64 v[214:215], v[208:209], 0, v[214:215]
	global_store_short v[214:215], v175, off
	v_mul_f32_e32 v175, v68, v206
	v_lshlrev_b64 v[214:215], 13, v[150:151]
	v_cvt_pk_bf16_f32 v175, v175, s0
	v_lshl_add_u64 v[214:215], v[208:209], 0, v[214:215]
	global_store_short v[214:215], v175, off
	v_mul_f32_e32 v175, v69, v206
	v_lshlrev_b64 v[214:215], 13, v[148:149]
	v_cvt_pk_bf16_f32 v175, v175, s0
	v_lshl_add_u64 v[214:215], v[208:209], 0, v[214:215]
	global_store_short v[214:215], v175, off
	v_mul_f32_e32 v175, v70, v206
	v_lshlrev_b64 v[214:215], 13, v[146:147]
	v_cvt_pk_bf16_f32 v175, v175, s0
	v_lshl_add_u64 v[214:215], v[208:209], 0, v[214:215]
	global_store_short v[214:215], v175, off
	v_mul_f32_e32 v175, v71, v206
	v_lshlrev_b64 v[214:215], 13, v[144:145]
	v_cvt_pk_bf16_f32 v175, v175, s0
	v_lshl_add_u64 v[214:215], v[208:209], 0, v[214:215]
	global_store_short v[214:215], v175, off
	v_mul_f32_e32 v175, v72, v206
	v_lshlrev_b64 v[214:215], 13, v[142:143]
	v_cvt_pk_bf16_f32 v175, v175, s0
	v_lshl_add_u64 v[214:215], v[208:209], 0, v[214:215]
	global_store_short v[214:215], v175, off
	v_mul_f32_e32 v175, v73, v206
	v_lshlrev_b64 v[214:215], 13, v[140:141]
	v_cvt_pk_bf16_f32 v175, v175, s0
	v_lshl_add_u64 v[214:215], v[208:209], 0, v[214:215]
	global_store_short v[214:215], v175, off
	v_mul_f32_e32 v175, v74, v206
	v_lshlrev_b64 v[214:215], 13, v[138:139]
	v_cvt_pk_bf16_f32 v175, v175, s0
	v_lshl_add_u64 v[214:215], v[208:209], 0, v[214:215]
	global_store_short v[214:215], v175, off
	v_mul_f32_e32 v175, v75, v206
	v_lshlrev_b64 v[214:215], 13, v[136:137]
	v_cvt_pk_bf16_f32 v175, v175, s0
	v_lshl_add_u64 v[214:215], v[208:209], 0, v[214:215]
	global_store_short v[214:215], v175, off
	v_mul_f32_e32 v175, v76, v206
	v_lshlrev_b64 v[214:215], 13, v[134:135]
	v_cvt_pk_bf16_f32 v175, v175, s0
	v_lshl_add_u64 v[214:215], v[208:209], 0, v[214:215]
	global_store_short v[214:215], v175, off
	v_mul_f32_e32 v175, v77, v206
	v_lshlrev_b64 v[214:215], 13, v[132:133]
	v_cvt_pk_bf16_f32 v175, v175, s0
	v_lshl_add_u64 v[214:215], v[208:209], 0, v[214:215]
	global_store_short v[214:215], v175, off
	v_mul_f32_e32 v175, v78, v206
	v_lshlrev_b64 v[214:215], 13, v[130:131]
	v_cvt_pk_bf16_f32 v175, v175, s0
	v_lshl_add_u64 v[214:215], v[208:209], 0, v[214:215]
	global_store_short v[214:215], v175, off
	v_mul_f32_e32 v175, v79, v206
	v_lshlrev_b64 v[206:207], 13, v[128:129]
	v_cvt_pk_bf16_f32 v175, v175, s0
	v_lshl_add_u64 v[206:207], v[208:209], 0, v[206:207]
	global_store_short v[206:207], v175, off

;     ...
;             for (int mi = 0; mi < MI; ++mi) {
;                 const int tok = tok0 + wr * C::WROWS + mi * 32 + li, tl = tok - half * HALF_T;
;                 const f32x4 s0 = *(const f32x4*)(SSQ + tok * 12 + 8);
;                 const float rs = __builtin_amdgcn_rsqf(((s0.x + s0.y) + (s0.z + s0.w)) * (1.f / 256.f) + EPS);
.LBB0_810:
	s_or_b64 exec, exec, s[4:5]
	v_add_u32_e32 v204, 0x180, v204
	v_ashrrev_i32_e32 v205, 31, v204
	v_lshl_add_u64 v[206:207], v[204:205], 2, s[10:11]
	v_mov_b32_e32 v206, v100
	v_mov_b32_e32 v207, v101
	v_mov_b32_e32 v208, v102
	v_mov_b32_e32 v209, v103
	v_add_f32_e32 v175, v206, v207
	v_add_f32_e32 v197, v208, v209
	v_add_f32_e32 v175, v175, v197
	v_fmamk_f32 v175, v175, 0x3b800000, v252
	v_rsq_f32_e32 v206, v175
	s_nop 0
	v_mul_f32_e32 v197, v48, v206
	v_mul_f32_e32 v175, v49, v206
	s_and_saveexec_b64 s[4:5], vcc
	s_xor_b64 s[4:5], exec, s[4:5]
	s_cbranch_execz .LBB0_812
; DI bf16_t f2bf(float x) { return (bf16_t)(pk2(x, 0.f) & 0xffffu); }
;     ...
;                     const int bl = tl >> 12, sq = tl & 4095;
; #pragma unroll
;                     for (int ni = 0; ni < 2; ++ni)
; #pragma unroll
;                         for (int r = 0; r < 16; ++r) {
;                             const int n = ncol0 - 2048 + ni * 32 + 8 * (r >> 2) + 4 * h + (r & 3);
;                             VT[((size_t)(bl * 2048 + n)) * 4096 + sq] = f2bf(acc[mi][ni][r] * rs);
;                         }
	s_movk_i32 s18, 0xfff
	v_bitop3_b32 v199, v246, s18, 64 bitop3:0xc8
	v_readlane_b32 s18, v254, 40
	v_lshlrev_b32_e32 v208, 1, v199
	v_mov_b32_e32 v209, v177
	v_readlane_b32 s19, v254, 41
	v_lshlrev_b64 v[214:215], 13, v[192:193]
	v_cvt_pk_bf16_f32 v197, v197, s0
	v_lshl_add_u64 v[208:209], s[18:19], 0, v[208:209]
	v_lshl_add_u64 v[214:215], v[208:209], 0, v[214:215]
	global_store_short v[214:215], v197, off
	v_lshlrev_b64 v[214:215], 13, v[194:195]
	v_cvt_pk_bf16_f32 v175, v175, s0
	v_lshl_add_u64 v[214:215], v[208:209], 0, v[214:215]
	global_store_short v[214:215], v175, off
	v_mul_f32_e32 v175, v50, v206
	v_lshlrev_b64 v[214:215], 13, v[190:191]
	v_cvt_pk_bf16_f32 v175, v175, s0
	v_lshl_add_u64 v[214:215], v[208:209], 0, v[214:215]
	global_store_short v[214:215], v175, off
	v_mul_f32_e32 v175, v51, v206
	v_lshlrev_b64 v[214:215], 13, v[188:189]
	v_cvt_pk_bf16_f32 v175, v175, s0
	v_lshl_add_u64 v[214:215], v[208:209], 0, v[214:215]
	global_store_short v[214:215], v175, off
	v_mul_f32_e32 v175, v52, v206
	v_lshlrev_b64 v[214:215], 13, v[186:187]
	v_cvt_pk_bf16_f32 v175, v175, s0
	v_lshl_add_u64 v[214:215], v[208:209], 0, v[214:215]
	global_store_short v[214:215], v175, off
	v_mul_f32_e32 v175, v53, v206
	v_lshlrev_b64 v[214:215], 13, v[184:185]
	v_cvt_pk_bf16_f32 v175, v175, s0
	v_lshl_add_u64 v[214:215], v[208:209], 0, v[214:215]
	global_store_short v[214:215], v175, off
	v_mul_f32_e32 v175, v54, v206
	v_lshlrev_b64 v[214:215], 13, v[182:183]
	v_cvt_pk_bf16_f32 v175, v175, s0
	v_lshl_add_u64 v[214:215], v[208:209], 0, v[214:215]
	global_store_short v[214:215], v175, off
	v_mul_f32_e32 v175, v55, v206
	v_lshlrev_b64 v[214:215], 13, v[180:181]
	v_cvt_pk_bf16_f32 v175, v175, s0
	v_lshl_add_u64 v[214:215], v[208:209], 0, v[214:215]
	global_store_short v[214:215], v175, off
	v_mul_f32_e32 v175, v56, v206
	v_lshlrev_b64 v[214:215], 13, v[178:179]
	v_cvt_pk_bf16_f32 v175, v175, s0
	v_lshl_add_u64 v[214:215], v[208:209], 0, v[214:215]
	global_store_short v[214:215], v175, off
	v_mul_f32_e32 v175, v57, v206
	v_lshlrev_b64 v[214:215], 13, v[172:173]
	v_cvt_pk_bf16_f32 v175, v175, s0
	v_lshl_add_u64 v[214:215], v[208:209], 0, v[214:215]
	global_store_short v[214:215], v175, off
	v_mul_f32_e32 v175, v58, v206
	v_lshlrev_b64 v[214:215], 13, v[170:171]
	v_cvt_pk_bf16_f32 v175, v175, s0
	v_lshl_add_u64 v[214:215], v[208:209], 0, v[214:215]
	global_store_short v[214:215], v175, off
	v_mul_f32_e32 v175, v59, v206
	v_lshlrev_b64 v[214:215], 13, v[168:169]
	v_cvt_pk_bf16_f32 v175, v175, s0
	v_lshl_add_u64 v[214:215], v[208:209], 0, v[214:215]
	global_store_short v[214:215], v175, off
	v_mul_f32_e32 v175, v60, v206
	v_lshlrev_b64 v[214:215], 13, v[166:167]
	v_cvt_pk_bf16_f32 v175, v175, s0
	v_lshl_add_u64 v[214:215], v[208:209], 0, v[214:215]
	global_store_short v[214:215], v175, off
	v_mul_f32_e32 v175, v61, v206
	v_lshlrev_b64 v[214:215], 13, v[164:165]
	v_cvt_pk_bf16_f32 v175, v175, s0
	v_lshl_add_u64 v[214:215], v[208:209], 0, v[214:215]
	global_store_short v[214:215], v175, off
	v_mul_f32_e32 v175, v62, v206
	v_lshlrev_b64 v[214:215], 13, v[162:163]
	v_cvt_pk_bf16_f32 v175, v175, s0
	v_lshl_add_u64 v[214:215], v[208:209], 0, v[214:215]
	global_store_short v[214:215], v175, off
	v_mul_f32_e32 v175, v63, v206
	v_lshlrev_b64 v[214:215], 13, v[160:161]
	v_cvt_pk_bf16_f32 v175, v175, s0
	v_lshl_add_u64 v[214:215], v[208:209], 0, v[214:215]
	global_store_short v[214:215], v175, off
	v_mul_f32_e32 v175, v32, v206
	v_lshlrev_b64 v[214:215], 13, v[158:159]
	v_cvt_pk_bf16_f32 v175, v175, s0
	v_lshl_add_u64 v[214:215], v[208:209], 0, v[214:215]
	global_store_short v[214:215], v175, off
	v_mul_f32_e32 v175, v33, v206
	v_lshlrev_b64 v[214:215], 13, v[156:157]
	v_cvt_pk_bf16_f32 v175, v175, s0
	v_lshl_add_u64 v[214:215], v[208:209], 0, v[214:215]
	global_store_short v[214:215], v175, off
	v_mul_f32_e32 v175, v34, v206
	v_lshlrev_b64 v[214:215], 13, v[154:155]
	v_cvt_pk_bf16_f32 v175, v175, s0
	v_lshl_add_u64 v[214:215], v[208:209], 0, v[214:215]
	global_store_short v[214:215], v175, off
	v_mul_f32_e32 v175, v35, v206
	v_lshlrev_b64 v[214:215], 13, v[152:153]
	v_cvt_pk_bf16_f32 v175, v175, s0
	v_lshl_add_u64 v[214:215], v[208:209], 0, v[214:215]
	global_store_short v[214:215], v175, off
	v_mul_f32_e32 v175, v36, v206
	v_lshlrev_b64 v[214:215], 13, v[150:151]
	v_cvt_pk_bf16_f32 v175, v175, s0
	v_lshl_add_u64 v[214:215], v[208:209], 0, v[214:215]
	global_store_short v[214:215], v175, off
	v_mul_f32_e32 v175, v37, v206
	v_lshlrev_b64 v[214:215], 13, v[148:149]
	v_cvt_pk_bf16_f32 v175, v175, s0
	v_lshl_add_u64 v[214:215], v[208:209], 0, v[214:215]
	global_store_short v[214:215], v175, off
	v_mul_f32_e32 v175, v38, v206
	v_lshlrev_b64 v[214:215], 13, v[146:147]
	v_cvt_pk_bf16_f32 v175, v175, s0
	v_lshl_add_u64 v[214:215], v[208:209], 0, v[214:215]
	global_store_short v[214:215], v175, off
	v_mul_f32_e32 v175, v39, v206
	v_lshlrev_b64 v[214:215], 13, v[144:145]
	v_cvt_pk_bf16_f32 v175, v175, s0
	v_lshl_add_u64 v[214:215], v[208:209], 0, v[214:215]
	global_store_short v[214:215], v175, off
	v_mul_f32_e32 v175, v40, v206
	v_lshlrev_b64 v[214:215], 13, v[142:143]
	v_cvt_pk_bf16_f32 v175, v175, s0
	v_lshl_add_u64 v[214:215], v[208:209], 0, v[214:215]
	global_store_short v[214:215], v175, off
	v_mul_f32_e32 v175, v41, v206
	v_lshlrev_b64 v[214:215], 13, v[140:141]
	v_cvt_pk_bf16_f32 v175, v175, s0
	v_lshl_add_u64 v[214:215], v[208:209], 0, v[214:215]
	global_store_short v[214:215], v175, off
	v_mul_f32_e32 v175, v42, v206
	v_lshlrev_b64 v[214:215], 13, v[138:139]
	v_cvt_pk_bf16_f32 v175, v175, s0
	v_lshl_add_u64 v[214:215], v[208:209], 0, v[214:215]
	global_store_short v[214:215], v175, off
	v_mul_f32_e32 v175, v43, v206
	v_lshlrev_b64 v[214:215], 13, v[136:137]
	v_cvt_pk_bf16_f32 v175, v175, s0
	v_lshl_add_u64 v[214:215], v[208:209], 0, v[214:215]
	global_store_short v[214:215], v175, off
	v_mul_f32_e32 v175, v44, v206
	v_lshlrev_b64 v[214:215], 13, v[134:135]
	v_cvt_pk_bf16_f32 v175, v175, s0
	v_lshl_add_u64 v[214:215], v[208:209], 0, v[214:215]
	global_store_short v[214:215], v175, off
	v_mul_f32_e32 v175, v45, v206
	v_lshlrev_b64 v[214:215], 13, v[132:133]
	v_cvt_pk_bf16_f32 v175, v175, s0
	v_lshl_add_u64 v[214:215], v[208:209], 0, v[214:215]
	global_store_short v[214:215], v175, off
	v_mul_f32_e32 v175, v46, v206
	v_lshlrev_b64 v[214:215], 13, v[130:131]
	v_cvt_pk_bf16_f32 v175, v175, s0
	v_lshl_add_u64 v[214:215], v[208:209], 0, v[214:215]
	global_store_short v[214:215], v175, off
	v_mul_f32_e32 v175, v47, v206
	v_lshlrev_b64 v[206:207], 13, v[128:129]
	v_cvt_pk_bf16_f32 v175, v175, s0
	v_lshl_add_u64 v[206:207], v[208:209], 0, v[206:207]
	global_store_short v[206:207], v175, off

;     ...
;             for (int mi = 0; mi < MI; ++mi) {
;                 const int tok = tok0 + wr * C::WROWS + mi * 32 + li, tl = tok - half * HALF_T;
;                 const f32x4 s0 = *(const f32x4*)(SSQ + tok * 12 + 8);
;                 const float rs = __builtin_amdgcn_rsqf(((s0.x + s0.y) + (s0.z + s0.w)) * (1.f / 256.f) + EPS);
.LBB0_814:
	s_or_b64 exec, exec, s[4:5]
	v_add_u32_e32 v204, 0x180, v204
	v_ashrrev_i32_e32 v205, 31, v204
	v_lshl_add_u64 v[204:205], v[204:205], 2, s[10:11]
	v_mov_b32_e32 v204, v104
	v_mov_b32_e32 v205, v105
	v_mov_b32_e32 v206, v106
	v_mov_b32_e32 v207, v107
	v_add_f32_e32 v175, v204, v205
	v_add_f32_e32 v197, v206, v207
	v_add_f32_e32 v175, v175, v197
	v_fmamk_f32 v175, v175, 0x3b800000, v252
	v_rsq_f32_e32 v204, v175
	s_nop 0
	v_mul_f32_e32 v197, v16, v204
	v_mul_f32_e32 v175, v17, v204
	s_and_saveexec_b64 s[4:5], vcc
	s_xor_b64 s[4:5], exec, s[4:5]
	s_cbranch_execz .LBB0_816
; DI bf16_t f2bf(float x) { return (bf16_t)(pk2(x, 0.f) & 0xffffu); }
;     ...
;                     const int bl = tl >> 12, sq = tl & 4095;
; #pragma unroll
;                     for (int ni = 0; ni < 2; ++ni)
; #pragma unroll
;                         for (int r = 0; r < 16; ++r) {
;                             const int n = ncol0 - 2048 + ni * 32 + 8 * (r >> 2) + 4 * h + (r & 3);
;                             VT[((size_t)(bl * 2048 + n)) * 4096 + sq] = f2bf(acc[mi][ni][r] * rs);
;                         }
	s_movk_i32 s18, 0xfff
	v_bitop3_b32 v174, v246, s18, v216 bitop3:0xc8
	v_readlane_b32 s18, v254, 40
	v_lshlrev_b32_e32 v176, 1, v174
	v_readlane_b32 s19, v254, 41
	v_lshlrev_b64 v[192:193], 13, v[192:193]
	v_cvt_pk_bf16_f32 v174, v197, s0
	v_lshl_add_u64 v[198:199], s[18:19], 0, v[176:177]
	v_lshl_add_u64 v[192:193], v[198:199], 0, v[192:193]
	global_store_short v[192:193], v174, off
	v_cvt_pk_bf16_f32 v176, v175, s0
	v_lshlrev_b64 v[174:175], 13, v[194:195]
	v_lshl_add_u64 v[174:175], v[198:199], 0, v[174:175]
	global_store_short v[174:175], v176, off
	v_mul_f32_e32 v174, v18, v204
	v_cvt_pk_bf16_f32 v176, v174, s0
	v_lshlrev_b64 v[174:175], 13, v[190:191]
	v_lshl_add_u64 v[174:175], v[198:199], 0, v[174:175]
	global_store_short v[174:175], v176, off
	v_mul_f32_e32 v174, v19, v204
	v_cvt_pk_bf16_f32 v176, v174, s0
	v_lshlrev_b64 v[174:175], 13, v[188:189]
	v_lshl_add_u64 v[174:175], v[198:199], 0, v[174:175]
	global_store_short v[174:175], v176, off
	v_mul_f32_e32 v174, v20, v204
	v_cvt_pk_bf16_f32 v176, v174, s0
	v_lshlrev_b64 v[174:175], 13, v[186:187]
	v_lshl_add_u64 v[174:175], v[198:199], 0, v[174:175]
	global_store_short v[174:175], v176, off
	v_mul_f32_e32 v174, v21, v204
	v_cvt_pk_bf16_f32 v176, v174, s0
	v_lshlrev_b64 v[174:175], 13, v[184:185]
	v_lshl_add_u64 v[174:175], v[198:199], 0, v[174:175]
	global_store_short v[174:175], v176, off
	v_mul_f32_e32 v174, v22, v204
	v_cvt_pk_bf16_f32 v176, v174, s0
	v_lshlrev_b64 v[174:175], 13, v[182:183]
	v_lshl_add_u64 v[174:175], v[198:199], 0, v[174:175]
	global_store_short v[174:175], v176, off
	v_mul_f32_e32 v174, v23, v204
	v_cvt_pk_bf16_f32 v176, v174, s0
	v_lshlrev_b64 v[174:175], 13, v[180:181]
	v_lshl_add_u64 v[174:175], v[198:199], 0, v[174:175]
	global_store_short v[174:175], v176, off
	v_mul_f32_e32 v174, v24, v204
	v_cvt_pk_bf16_f32 v176, v174, s0
	v_lshlrev_b64 v[174:175], 13, v[178:179]
	v_lshl_add_u64 v[174:175], v[198:199], 0, v[174:175]
	global_store_short v[174:175], v176, off
	v_mul_f32_e32 v174, v25, v204
	v_lshlrev_b64 v[172:173], 13, v[172:173]
	v_cvt_pk_bf16_f32 v174, v174, s0
	v_lshl_add_u64 v[172:173], v[198:199], 0, v[172:173]
	global_store_short v[172:173], v174, off
	v_mul_f32_e32 v172, v26, v204
	v_lshlrev_b64 v[170:171], 13, v[170:171]
	v_cvt_pk_bf16_f32 v172, v172, s0
	v_lshl_add_u64 v[170:171], v[198:199], 0, v[170:171]
	global_store_short v[170:171], v172, off
	v_mul_f32_e32 v170, v27, v204
	v_lshlrev_b64 v[168:169], 13, v[168:169]
	v_cvt_pk_bf16_f32 v170, v170, s0
	v_lshl_add_u64 v[168:169], v[198:199], 0, v[168:169]
	global_store_short v[168:169], v170, off
	v_mul_f32_e32 v168, v28, v204
	v_lshlrev_b64 v[166:167], 13, v[166:167]
	v_cvt_pk_bf16_f32 v168, v168, s0
	v_lshl_add_u64 v[166:167], v[198:199], 0, v[166:167]
	global_store_short v[166:167], v168, off
	v_mul_f32_e32 v166, v29, v204
	v_lshlrev_b64 v[164:165], 13, v[164:165]
	v_cvt_pk_bf16_f32 v166, v166, s0
	v_lshl_add_u64 v[164:165], v[198:199], 0, v[164:165]
	global_store_short v[164:165], v166, off
	v_mul_f32_e32 v164, v30, v204
	v_lshlrev_b64 v[162:163], 13, v[162:163]
	v_cvt_pk_bf16_f32 v164, v164, s0
	v_lshl_add_u64 v[162:163], v[198:199], 0, v[162:163]
	global_store_short v[162:163], v164, off
	v_mul_f32_e32 v162, v31, v204
	v_lshlrev_b64 v[160:161], 13, v[160:161]
	v_cvt_pk_bf16_f32 v162, v162, s0
	v_lshl_add_u64 v[160:161], v[198:199], 0, v[160:161]
	global_store_short v[160:161], v162, off
	v_mul_f32_e32 v160, v0, v204
	v_lshlrev_b64 v[158:159], 13, v[158:159]
	v_cvt_pk_bf16_f32 v160, v160, s0
	v_lshl_add_u64 v[158:159], v[198:199], 0, v[158:159]
	global_store_short v[158:159], v160, off
	v_mul_f32_e32 v158, v1, v204
	v_lshlrev_b64 v[156:157], 13, v[156:157]
	v_cvt_pk_bf16_f32 v158, v158, s0
	v_lshl_add_u64 v[156:157], v[198:199], 0, v[156:157]
	global_store_short v[156:157], v158, off
	v_mul_f32_e32 v156, v2, v204
	v_lshlrev_b64 v[154:155], 13, v[154:155]
	v_cvt_pk_bf16_f32 v156, v156, s0
	v_lshl_add_u64 v[154:155], v[198:199], 0, v[154:155]
	global_store_short v[154:155], v156, off
	v_mul_f32_e32 v154, v3, v204
	v_lshlrev_b64 v[152:153], 13, v[152:153]
	v_cvt_pk_bf16_f32 v154, v154, s0
	v_lshl_add_u64 v[152:153], v[198:199], 0, v[152:153]
	global_store_short v[152:153], v154, off
	v_mul_f32_e32 v152, v4, v204
	v_lshlrev_b64 v[150:151], 13, v[150:151]
	v_cvt_pk_bf16_f32 v152, v152, s0
	v_lshl_add_u64 v[150:151], v[198:199], 0, v[150:151]
	global_store_short v[150:151], v152, off
	v_mul_f32_e32 v150, v5, v204
	v_lshlrev_b64 v[148:149], 13, v[148:149]
	v_cvt_pk_bf16_f32 v150, v150, s0
	v_lshl_add_u64 v[148:149], v[198:199], 0, v[148:149]
	global_store_short v[148:149], v150, off
	v_mul_f32_e32 v148, v6, v204
	v_lshlrev_b64 v[146:147], 13, v[146:147]
	v_cvt_pk_bf16_f32 v148, v148, s0
	v_lshl_add_u64 v[146:147], v[198:199], 0, v[146:147]
	global_store_short v[146:147], v148, off
	v_mul_f32_e32 v146, v7, v204
	v_lshlrev_b64 v[144:145], 13, v[144:145]
	v_cvt_pk_bf16_f32 v146, v146, s0
	v_lshl_add_u64 v[144:145], v[198:199], 0, v[144:145]
	global_store_short v[144:145], v146, off
	v_mul_f32_e32 v144, v8, v204
	v_lshlrev_b64 v[142:143], 13, v[142:143]
	v_cvt_pk_bf16_f32 v144, v144, s0
	v_lshl_add_u64 v[142:143], v[198:199], 0, v[142:143]
	global_store_short v[142:143], v144, off
	v_mul_f32_e32 v142, v9, v204
	v_lshlrev_b64 v[140:141], 13, v[140:141]
	v_cvt_pk_bf16_f32 v142, v142, s0
	v_lshl_add_u64 v[140:141], v[198:199], 0, v[140:141]
	global_store_short v[140:141], v142, off
	v_mul_f32_e32 v140, v10, v204
	v_lshlrev_b64 v[138:139], 13, v[138:139]
	v_cvt_pk_bf16_f32 v140, v140, s0
	v_lshl_add_u64 v[138:139], v[198:199], 0, v[138:139]
	global_store_short v[138:139], v140, off
	v_mul_f32_e32 v138, v11, v204
	v_lshlrev_b64 v[136:137], 13, v[136:137]
	v_cvt_pk_bf16_f32 v138, v138, s0
	v_lshl_add_u64 v[136:137], v[198:199], 0, v[136:137]
	global_store_short v[136:137], v138, off
	v_mul_f32_e32 v136, v12, v204
	v_lshlrev_b64 v[134:135], 13, v[134:135]
	v_cvt_pk_bf16_f32 v136, v136, s0
	v_lshl_add_u64 v[134:135], v[198:199], 0, v[134:135]
	global_store_short v[134:135], v136, off
	v_mul_f32_e32 v134, v13, v204
	v_lshlrev_b64 v[132:133], 13, v[132:133]
	v_cvt_pk_bf16_f32 v134, v134, s0
	v_lshl_add_u64 v[132:133], v[198:199], 0, v[132:133]
	global_store_short v[132:133], v134, off
	v_mul_f32_e32 v132, v14, v204
	v_lshlrev_b64 v[130:131], 13, v[130:131]
	v_cvt_pk_bf16_f32 v132, v132, s0
	v_lshl_add_u64 v[130:131], v[198:199], 0, v[130:131]
	global_store_short v[130:131], v132, off
	v_mul_f32_e32 v130, v15, v204
	v_lshlrev_b64 v[128:129], 13, v[128:129]
	v_cvt_pk_bf16_f32 v130, v130, s0
	v_lshl_add_u64 v[128:129], v[198:199], 0, v[128:129]
	global_store_short v[128:129], v130, off
